# VAR1 band attention: K fragments, rel-pos bias and V fragments of a key tile read together (unique registers), counted waits; MFMAs back-to-back
# speedup vs baseline: 1.0020x; 1.0020x over previous
; #define LAS __attribute__((address_space(3)))
; __device__ __forceinline__ float pair_max(float v) { float a, b; lohi(v, a, b); return fmaxf(a, b); }
; __device__ __forceinline__ void softmax_pv(f32x16& p0, f32x16& p1, float& m, float& l, f32x16 (&o)[2], LAS float* wsf, const LAS unsigned char* vp, int r32, int hi) {
;     float rm = fmaxf(p0[0], p1[0]);
; #pragma unroll
;     for (int r = 1; r < 16; ++r) rm = fmaxf(rm, fmaxf(p0[r], p1[r]));
;     rm = pair_max(rm);
;     if (__all(rm - m < -151.0f)) return;
;     const float mnew = fmaxf(m, rm), alpha = __builtin_amdgcn_exp2f(m - mnew);
;     m = mnew;
;     float s = 0.f;
; #pragma unroll
;     for (int r = 0; r < 16; ++r) { p0[r] = __builtin_amdgcn_exp2f(p0[r] - mnew); p1[r] = __builtin_amdgcn_exp2f(p1[r] - mnew); s += p0[r] + p1[r]; }
;     l = l * alpha + s;
;     if (__any(alpha != 1.0f)) {
;         if (hi == 0) wsf[r32] = alpha;
; #pragma unroll
;         for (int r = 0; r < 16; ++r) { const float f = wsf[(r & 3) + 8 * (r >> 2) + 4 * hi]; o[0][r] *= f; o[1][r] *= f; }
; template <int VAR>
; __device__ __forceinline__ void attn_unit(LAS unsigned char* lds, const AttnArgs& A, int b, int h, int qb, const int tid) {
;     ...
;                 for (int mp = 0; mp < 2; ++mp) {
;                     f32x16 p0, p1;
; #pragma unroll
;                     for (int r = 0; r < 16; ++r) { p0[r] = 0.f; p1[r] = 0.f; }
;                     __builtin_amdgcn_s_setprio(1);
; #pragma unroll
;                     for (int dd = 0; dd < 2; ++dd) {
;                         const int d0 = 2 * mp + dd;
;                         const bf16x8 b0 = *(const LAS bf16x8*)(kb + d0 * 2048), b1 = *(const LAS bf16x8*)(kb + d0 * 2048 + 512);
;                         p0 = __builtin_amdgcn_mfma_f32_32x32x16_bf16(b0, qr[d0], p0, 0, 0, 0);
;                         p1 = __builtin_amdgcn_mfma_f32_32x32x16_bf16(b1, qr[d0], p1, 0, 0, 0);
;                     }
;                     __builtin_amdgcn_s_setprio(0);
; #pragma unroll
;                     for (int r = 0; r < 16; ++r) {
;                         const float c0 = (float)((r & 3) + 8 * (r >> 2));
;                         p0[r] = __builtin_fmaf(-slope2, __builtin_fabsf(tb - c0), p0[r]);
;                         p1[r] = __builtin_fmaf(-slope2, __builtin_fabsf(tb - (c0 + 32.0f)), p1[r]);
;                     }
.LBB0_453:
	s_add_i32 s38, s84, 2
	s_and_b32 s71, s70, 1
	s_cmp_gt_i32 s38, s81
	s_cselect_b64 s[38:39], -1, 0
	s_or_b64 s[38:39], s[38:39], s[12:13]
	s_and_b64 vcc, exec, s[38:39]
	s_cbranch_vccnz .LBB0_460
	v_add_u32_e32 v66, v140, v141
	v_cvt_f32_i32_e32 v134, v66
	s_lshl_b32 s50, s71, 13
	v_add_u32_e32 v145, s50, v136
	s_setprio 1
	ds_read_b128 v[66:69], v145
	ds_read_b128 v[82:85], v145 offset:512
	ds_read_b128 v[146:149], v145 offset:2048
	s_waitcnt lgkmcnt(2)
	v_mfma_f32_32x32x16_bf16 v[66:81], v[66:69], v[98:101], 0
	s_waitcnt lgkmcnt(0)
	v_mfma_f32_32x32x16_bf16 v[66:81], v[146:149], v[102:105], v[66:81]
	ds_read_b128 v[146:149], v145 offset:2560
	v_mfma_f32_32x32x16_bf16 v[82:97], v[82:85], v[98:101], 0
	s_waitcnt lgkmcnt(0)
	v_mfma_f32_32x32x16_bf16 v[82:97], v[146:149], v[102:105], v[82:97]
	s_setprio 0
	v_add_f32_e32 v147, -1.0, v134
	v_add_f32_e32 v148, 0xc2040000, v134
	v_add_f32_e32 v146, 0xc2000000, v134
	s_nop 3
	v_fma_f32 v213, v138, |v147|, v67
	s_nop 2
	v_fma_f32 v214, v138, |v148|, v83
	v_add_f32_e32 v149, -2.0, v134
	v_add_f32_e32 v150, 0xc2080000, v134
	v_add_f32_e32 v151, 0xc0400000, v134
	v_add_f32_e32 v152, 0xc20c0000, v134
	v_add_f32_e32 v173, 0xc1800000, v134
	v_add_f32_e32 v182, 0xc1980000, v134
	v_fma_f32 v215, v138, |v134|, v66
	v_fma_f32 v216, v138, |v146|, v82
	v_fma_f32 v211, v138, |v149|, v68
	v_fma_f32 v212, v138, |v150|, v84
	v_fma_f32 v209, v138, |v151|, v69
	v_fma_f32 v210, v138, |v152|, v85
	v_add_f32_e32 v153, 0xc1000000, v134
	v_add_f32_e32 v166, 0xc2200000, v134
	v_add_f32_e32 v167, 0xc1100000, v134
	v_add_f32_e32 v168, 0xc2240000, v134
	v_add_f32_e32 v169, 0xc1200000, v134
	v_fma_f32 v85, v138, |v173|, v74
	v_fma_f32 v74, v138, |v182|, v77
	v_add_f32_e32 v184, 0xc1c00000, v134
	v_add_f32_e32 v186, 0xc1c80000, v134
	v_max_f32_e32 v77, v213, v214
	v_fma_f32 v207, v138, |v153|, v70
	v_fma_f32 v208, v138, |v166|, v86
	v_fma_f32 v205, v138, |v167|, v71
	v_fma_f32 v206, v138, |v168|, v87
	v_fma_f32 v192, v138, |v169|, v72
	v_add_f32_e32 v170, 0xc2280000, v134
	v_add_f32_e32 v171, 0xc1300000, v134
	v_add_f32_e32 v172, 0xc22c0000, v134
	v_fma_f32 v72, v138, |v184|, v78
	v_fma_f32 v70, v138, |v186|, v79
	v_max3_f32 v77, v215, v216, v77
	v_max_f32_e32 v78, v211, v212
	v_max_f32_e32 v79, v209, v210
	v_fma_f32 v193, v138, |v170|, v88
	v_fma_f32 v87, v138, |v171|, v73
	v_fma_f32 v88, v138, |v172|, v89
	v_add_f32_e32 v177, 0xc2400000, v134
	v_add_f32_e32 v178, 0xc1880000, v134
	v_add_f32_e32 v179, 0xc2440000, v134
	v_max3_f32 v77, v77, v78, v79
	v_max_f32_e32 v78, v207, v208
	v_max_f32_e32 v79, v205, v206
	v_fma_f32 v86, v138, |v177|, v90
	v_fma_f32 v83, v138, |v178|, v75
	v_fma_f32 v84, v138, |v179|, v91
	v_add_f32_e32 v180, 0xc1900000, v134
	v_add_f32_e32 v181, 0xc2480000, v134
	v_add_f32_e32 v183, 0xc24c0000, v134
	v_max3_f32 v77, v77, v78, v79
	v_max_f32_e32 v78, v192, v193
	v_max_f32_e32 v79, v87, v88
	v_fma_f32 v76, v138, |v180|, v76
	v_fma_f32 v82, v138, |v181|, v92
	v_fma_f32 v75, v138, |v183|, v93
	v_add_f32_e32 v185, 0xc2600000, v134
	v_add_f32_e32 v187, 0xc2640000, v134
	v_max3_f32 v77, v77, v78, v79
	v_max_f32_e32 v78, v85, v86
	v_max_f32_e32 v79, v83, v84
	v_fma_f32 v73, v138, |v185|, v94
	v_fma_f32 v71, v138, |v187|, v95
	v_add_f32_e32 v188, 0xc1d00000, v134
	v_add_f32_e32 v189, 0xc2680000, v134
	v_add_f32_e32 v190, 0xc1d80000, v134
	v_add_f32_e32 v191, 0xc26c0000, v134
	v_max3_f32 v77, v77, v78, v79
	v_max_f32_e32 v78, v76, v82
	v_max_f32_e32 v79, v74, v75
	v_fma_f32 v68, v138, |v188|, v80
	v_fma_f32 v69, v138, |v189|, v96
	v_fma_f32 v66, v138, |v190|, v81
	v_fma_f32 v67, v138, |v191|, v97
	v_max3_f32 v77, v77, v78, v79
	v_max_f32_e32 v78, v72, v73
	v_max_f32_e32 v79, v70, v71
	v_max3_f32 v77, v77, v78, v79
	v_max_f32_e32 v78, v68, v69
	v_max_f32_e32 v79, v66, v67
	v_max3_f32 v77, v77, v78, v79
	v_mov_b32_e32 v78, v77
	s_nop 1
	v_permlane32_swap_b32_e32 v77, v78
	v_max_f32_e32 v78, v78, v78
	v_max_f32_e32 v77, v77, v77
	v_max_f32_e32 v77, v77, v78
	v_sub_f32_e32 v78, v77, v217
	v_cmp_gt_f32_e32 vcc, s36, v78
	s_cmp_eq_u64 vcc, exec
	s_cbranch_scc1 .LBB0_461
	v_max_f32_e32 v77, v77, v77
	v_max_f32_e32 v78, v217, v217
	v_max_f32_e32 v135, v78, v77
	v_sub_f32_e32 v77, v217, v135
	v_exp_f32_e32 v77, v77
	s_nop 0
	v_cmp_neq_f32_e32 vcc, 1.0, v77
	s_cbranch_vccz .LBB0_459
	s_and_saveexec_b64 s[12:13], s[8:9]
	ds_write_b32 v139, v77 offset:36864
	s_or_b64 exec, exec, s[12:13]
	v_add_u32_e32 v89, s69, v0
	ds_read_b128 v[78:81], v89 offset:36960
	ds_read_b128 v[90:93], v89 offset:36928
	ds_read_b128 v[94:97], v89 offset:36896
	ds_read_b128 v[218:221], v89 offset:36864
	s_waitcnt lgkmcnt(3)
	v_pk_mul_f32 v[62:63], v[62:63], v[78:79]
	s_waitcnt lgkmcnt(2)
	v_pk_mul_f32 v[58:59], v[58:59], v[90:91]
	s_waitcnt lgkmcnt(1)
	v_pk_mul_f32 v[54:55], v[54:55], v[94:95]
	v_pk_mul_f32 v[64:65], v[64:65], v[80:81]
	v_pk_mul_f32 v[60:61], v[60:61], v[92:93]
	v_pk_mul_f32 v[56:57], v[56:57], v[96:97]
	s_waitcnt lgkmcnt(0)
	v_pk_mul_f32 v[52:53], v[52:53], v[220:221]
	v_pk_mul_f32 v[50:51], v[50:51], v[218:219]
	v_pk_mul_f32 v[46:47], v[46:47], v[78:79]
	v_pk_mul_f32 v[42:43], v[42:43], v[90:91]
	v_pk_mul_f32 v[38:39], v[38:39], v[94:95]
	v_pk_mul_f32 v[48:49], v[48:49], v[80:81]
	v_pk_mul_f32 v[44:45], v[44:45], v[92:93]
	v_pk_mul_f32 v[40:41], v[40:41], v[96:97]
	v_pk_mul_f32 v[36:37], v[36:37], v[220:221]
	v_pk_mul_f32 v[34:35], v[34:35], v[218:219]
; #define LAS __attribute__((address_space(3)))
; __device__ __forceinline__ unsigned cvtpk(float lo, float hi) { f32x2_t v = {lo, hi}; bf16x2_t b = __builtin_convertvector(v, bf16x2_t); return __builtin_bit_cast(unsigned, b); }
; __device__ __forceinline__ s16x4 vtr(const LAS unsigned char* p) { return __builtin_bit_cast(s16x4, __builtin_amdgcn_ds_read_tr16_b64_v4i16((LAS v4i16_t*)p)); }
; __device__ __forceinline__ void pv(f32x16 (&o)[2], const LAS unsigned char* vp, const f32x16& p0, const f32x16& p1) {
;     u32x4 pw[4];
;     pw[0] = (u32x4){cvtpk(p0[0], p0[1]), cvtpk(p0[2], p0[3]), cvtpk(p0[4], p0[5]), cvtpk(p0[6], p0[7])};
;     pw[1] = (u32x4){cvtpk(p0[8], p0[9]), cvtpk(p0[10], p0[11]), cvtpk(p0[12], p0[13]), cvtpk(p0[14], p0[15])};
;     pw[2] = (u32x4){cvtpk(p1[0], p1[1]), cvtpk(p1[2], p1[3]), cvtpk(p1[4], p1[5]), cvtpk(p1[6], p1[7])};
;     pw[3] = (u32x4){cvtpk(p1[8], p1[9]), cvtpk(p1[10], p1[11]), cvtpk(p1[12], p1[13]), cvtpk(p1[14], p1[15])};
;     __builtin_amdgcn_s_setprio(1);
; #pragma unroll
;     for (int dh = 0; dh < 2; ++dh)
; #pragma unroll
;         for (int ks = 0; ks < 4; ++ks) {
;             const s16x4 lo = vtr(vp + dh * 4096 + ks * 1024), hi_ = vtr(vp + dh * 4096 + ks * 1024 + 512);
;             const bf16x8 vf = __builtin_shufflevector(lo, hi_, 0, 1, 2, 3, 4, 5, 6, 7);
;             o[dh] = __builtin_amdgcn_mfma_f32_32x32x16_bf16(__builtin_bit_cast(bf16x8, pw[ks]), vf, o[dh], 0, 0, 0);
;         }
;     __builtin_amdgcn_s_setprio(0);
; __device__ __forceinline__ void softmax_pv(f32x16& p0, f32x16& p1, float& m, float& l, f32x16 (&o)[2], LAS float* wsf, const LAS unsigned char* vp, int r32, int hi) {
;     ...
;     float s = 0.f;
; #pragma unroll
;     for (int r = 0; r < 16; ++r) { p0[r] = __builtin_amdgcn_exp2f(p0[r] - mnew); p1[r] = __builtin_amdgcn_exp2f(p1[r] - mnew); s += p0[r] + p1[r]; }
;     l = l * alpha + s;
.LBB0_459:
	v_sub_f32_e32 v78, v215, v135
	v_sub_f32_e32 v79, v216, v135
	v_exp_f32_e32 v78, v78
	v_exp_f32_e32 v79, v79
	v_sub_f32_e32 v80, v213, v135
	v_sub_f32_e32 v81, v214, v135
	v_exp_f32_e32 v80, v80
	v_exp_f32_e32 v81, v81
	v_sub_f32_e32 v91, v211, v135
	v_sub_f32_e32 v92, v212, v135
	v_exp_f32_e32 v91, v91
	v_exp_f32_e32 v92, v92
	v_sub_f32_e32 v93, v209, v135
	v_sub_f32_e32 v94, v210, v135
	v_exp_f32_e32 v93, v93
	v_exp_f32_e32 v94, v94
	v_sub_f32_e32 v95, v207, v135
	v_sub_f32_e32 v96, v208, v135
	v_add_f32_e32 v89, v78, v79
	v_exp_f32_e32 v95, v95
	v_exp_f32_e32 v96, v96
	v_sub_f32_e32 v97, v205, v135
	v_sub_f32_e32 v194, v206, v135
	v_add_f32_e32 v89, 0, v89
	v_add_f32_e32 v90, v80, v81
	v_exp_f32_e32 v97, v97
	v_exp_f32_e32 v194, v194
	v_sub_f32_e32 v192, v192, v135
	v_sub_f32_e32 v193, v193, v135
	v_add_f32_e32 v89, v90, v89
	v_add_f32_e32 v90, v91, v92
	v_exp_f32_e32 v192, v192
	v_exp_f32_e32 v193, v193
	v_sub_f32_e32 v87, v87, v135
	v_sub_f32_e32 v88, v88, v135
	v_add_f32_e32 v89, v90, v89
	v_add_f32_e32 v90, v93, v94
	v_exp_f32_e32 v87, v87
	v_exp_f32_e32 v88, v88
	v_sub_f32_e32 v85, v85, v135
	v_sub_f32_e32 v86, v86, v135
	v_add_f32_e32 v89, v90, v89
	v_add_f32_e32 v90, v95, v96
	v_exp_f32_e32 v85, v85
	v_exp_f32_e32 v86, v86
	v_sub_f32_e32 v83, v83, v135
	v_sub_f32_e32 v84, v84, v135
	v_add_f32_e32 v89, v90, v89
	v_add_f32_e32 v90, v97, v194
	v_exp_f32_e32 v83, v83
	v_exp_f32_e32 v84, v84
	v_sub_f32_e32 v76, v76, v135
	v_sub_f32_e32 v82, v82, v135
	v_add_f32_e32 v89, v90, v89
	v_add_f32_e32 v90, v192, v193
	v_exp_f32_e32 v76, v76
	v_exp_f32_e32 v82, v82
	v_sub_f32_e32 v74, v74, v135
	v_sub_f32_e32 v75, v75, v135
	v_add_f32_e32 v89, v90, v89
	v_add_f32_e32 v90, v87, v88
	v_exp_f32_e32 v74, v74
	v_exp_f32_e32 v195, v75
	v_add_f32_e32 v89, v90, v89
	v_add_f32_e32 v90, v85, v86
	v_add_f32_e32 v89, v90, v89
	v_add_f32_e32 v90, v83, v84
	v_add_f32_e32 v75, v90, v89
	v_add_f32_e32 v89, v76, v82
	v_sub_f32_e32 v72, v72, v135
	v_sub_f32_e32 v73, v73, v135
	v_sub_f32_e32 v70, v70, v135
	v_add_f32_e32 v75, v89, v75
	v_add_f32_e32 v89, v74, v195
	v_exp_f32_e32 v72, v72
	v_exp_f32_e32 v90, v73
	v_exp_f32_e32 v73, v70
	v_sub_f32_e32 v70, v71, v135
	v_sub_f32_e32 v68, v68, v135
	v_exp_f32_e32 v205, v70
	v_add_f32_e32 v70, v89, v75
	v_exp_f32_e32 v75, v68
	v_sub_f32_e32 v68, v69, v135
	v_sub_f32_e32 v66, v66, v135
	v_exp_f32_e32 v89, v68
	v_exp_f32_e32 v206, v66
	v_sub_f32_e32 v66, v67, v135
	v_exp_f32_e32 v207, v66
	v_add_f32_e32 v71, v72, v90
	v_add_f32_e32 v70, v71, v70
	v_add_f32_e32 v71, v73, v205
	v_add_f32_e32 v66, v71, v70
	v_add_f32_e32 v67, v75, v89
	v_add_f32_e32 v66, v67, v66
	v_add_f32_e32 v67, v206, v207
	v_add_f32_e32 v208, v67, v66
	v_fmac_f32_e32 v208, v143, v77
	v_cvt_pk_bf16_f32 v66, v78, v80
	v_cvt_pk_bf16_f32 v67, v91, v93
	v_cvt_pk_bf16_f32 v68, v95, v97
	v_cvt_pk_bf16_f32 v69, v192, v87
	v_cvt_pk_bf16_f32 v70, v85, v83
	v_cvt_pk_bf16_f32 v71, v76, v74
	v_cvt_pk_bf16_f32 v72, v72, v73
	v_cvt_pk_bf16_f32 v73, v75, v206
	v_cvt_pk_bf16_f32 v74, v79, v81
	v_cvt_pk_bf16_f32 v75, v92, v94
	v_cvt_pk_bf16_f32 v76, v96, v194
	v_cvt_pk_bf16_f32 v77, v193, v88
	v_cvt_pk_bf16_f32 v78, v86, v84
	v_cvt_pk_bf16_f32 v79, v82, v195
	v_cvt_pk_bf16_f32 v80, v90, v205
	v_cvt_pk_bf16_f32 v81, v89, v207
	s_setprio 1
	v_add_u32_e32 v86, s50, v137
	ds_read_b64_tr_b16 v[82:83], v86 offset:16384
	ds_read_b64_tr_b16 v[84:85], v86 offset:16896
	s_waitcnt lgkmcnt(0)
	v_mfma_f32_32x32x16_bf16 v[50:65], v[66:69], v[82:85], v[50:65]
	ds_read_b64_tr_b16 v[82:83], v86 offset:17408
	ds_read_b64_tr_b16 v[84:85], v86 offset:17920
	s_waitcnt lgkmcnt(0)
	v_mfma_f32_32x32x16_bf16 v[50:65], v[70:73], v[82:85], v[50:65]
	ds_read_b64_tr_b16 v[82:83], v86 offset:18432
	ds_read_b64_tr_b16 v[84:85], v86 offset:18944
	s_waitcnt lgkmcnt(0)
	v_mfma_f32_32x32x16_bf16 v[50:65], v[74:77], v[82:85], v[50:65]
	ds_read_b64_tr_b16 v[82:83], v86 offset:19456
	ds_read_b64_tr_b16 v[84:85], v86 offset:19968
	s_waitcnt lgkmcnt(0)
	v_mfma_f32_32x32x16_bf16 v[50:65], v[78:81], v[82:85], v[50:65]
	ds_read_b64_tr_b16 v[82:83], v86 offset:20480
	ds_read_b64_tr_b16 v[84:85], v86 offset:20992
	s_waitcnt lgkmcnt(0)
	v_mfma_f32_32x32x16_bf16 v[34:49], v[66:69], v[82:85], v[34:49]
	ds_read_b64_tr_b16 v[66:67], v86 offset:21504
	ds_read_b64_tr_b16 v[68:69], v86 offset:22016
	s_waitcnt lgkmcnt(0)
	v_mfma_f32_32x32x16_bf16 v[34:49], v[70:73], v[66:69], v[34:49]
	ds_read_b64_tr_b16 v[66:67], v86 offset:22528
	ds_read_b64_tr_b16 v[68:69], v86 offset:23040
	s_waitcnt lgkmcnt(0)
	v_mfma_f32_32x32x16_bf16 v[34:49], v[74:77], v[66:69], v[34:49]
	ds_read_b64_tr_b16 v[66:67], v86 offset:23552
	ds_read_b64_tr_b16 v[68:69], v86 offset:24064
	s_waitcnt lgkmcnt(0)
	v_mfma_f32_32x32x16_bf16 v[34:49], v[78:81], v[66:69], v[34:49]
	s_setprio 0
	v_mov_b32_e32 v143, v208
	s_branch .LBB0_462

; #define LAS __attribute__((address_space(3)))
; __device__ __forceinline__ unsigned cvtpk(float lo, float hi) { f32x2_t v = {lo, hi}; bf16x2_t b = __builtin_convertvector(v, bf16x2_t); return __builtin_bit_cast(unsigned, b); }
; __device__ __forceinline__ s16x4 vtr(const LAS unsigned char* p) { return __builtin_bit_cast(s16x4, __builtin_amdgcn_ds_read_tr16_b64_v4i16((LAS v4i16_t*)p)); }
; __device__ __forceinline__ void pv(f32x16 (&o)[2], const LAS unsigned char* vp, const f32x16& p0, const f32x16& p1) {
;     u32x4 pw[4];
;     pw[0] = (u32x4){cvtpk(p0[0], p0[1]), cvtpk(p0[2], p0[3]), cvtpk(p0[4], p0[5]), cvtpk(p0[6], p0[7])};
;     pw[1] = (u32x4){cvtpk(p0[8], p0[9]), cvtpk(p0[10], p0[11]), cvtpk(p0[12], p0[13]), cvtpk(p0[14], p0[15])};
;     pw[2] = (u32x4){cvtpk(p1[0], p1[1]), cvtpk(p1[2], p1[3]), cvtpk(p1[4], p1[5]), cvtpk(p1[6], p1[7])};
;     pw[3] = (u32x4){cvtpk(p1[8], p1[9]), cvtpk(p1[10], p1[11]), cvtpk(p1[12], p1[13]), cvtpk(p1[14], p1[15])};
;     __builtin_amdgcn_s_setprio(1);
; #pragma unroll
;     for (int dh = 0; dh < 2; ++dh)
; #pragma unroll
;         for (int ks = 0; ks < 4; ++ks) {
;             const s16x4 lo = vtr(vp + dh * 4096 + ks * 1024), hi_ = vtr(vp + dh * 4096 + ks * 1024 + 512);
;             const bf16x8 vf = __builtin_shufflevector(lo, hi_, 0, 1, 2, 3, 4, 5, 6, 7);
;             o[dh] = __builtin_amdgcn_mfma_f32_32x32x16_bf16(__builtin_bit_cast(bf16x8, pw[ks]), vf, o[dh], 0, 0, 0);
;         }
;     __builtin_amdgcn_s_setprio(0);
; __device__ __forceinline__ void softmax_pv(f32x16& p0, f32x16& p1, float& m, float& l, f32x16 (&o)[2], LAS float* wsf, const LAS unsigned char* vp, int r32, int hi) {
;     ...
;     float s = 0.f;
; #pragma unroll
;     for (int r = 0; r < 16; ++r) { p0[r] = __builtin_amdgcn_exp2f(p0[r] - mnew); p1[r] = __builtin_amdgcn_exp2f(p1[r] - mnew); s += p0[r] + p1[r]; }
;     l = l * alpha + s;
.LBB0_467:
	v_sub_f32_e32 v78, v209, v134
	v_sub_f32_e32 v79, v208, v134
	v_exp_f32_e32 v78, v78
	v_exp_f32_e32 v79, v79
	v_sub_f32_e32 v80, v207, v134
	v_sub_f32_e32 v81, v206, v134
	v_exp_f32_e32 v80, v80
	v_exp_f32_e32 v81, v81
	v_sub_f32_e32 v91, v205, v134
	v_sub_f32_e32 v92, v193, v134
	v_exp_f32_e32 v91, v91
	v_exp_f32_e32 v92, v92
	v_sub_f32_e32 v93, v192, v134
	v_sub_f32_e32 v94, v151, v134
	v_exp_f32_e32 v93, v93
	v_exp_f32_e32 v94, v94
	v_sub_f32_e32 v95, v150, v134
	v_sub_f32_e32 v96, v149, v134
	v_add_f32_e32 v89, v78, v79
	v_exp_f32_e32 v95, v95
	v_exp_f32_e32 v96, v96
	v_sub_f32_e32 v97, v148, v134
	v_sub_f32_e32 v144, v147, v134
	v_add_f32_e32 v89, 0, v89
	v_add_f32_e32 v90, v80, v81
	v_exp_f32_e32 v97, v97
	v_exp_f32_e32 v144, v144
	v_sub_f32_e32 v146, v146, v134
	v_sub_f32_e32 v145, v145, v134
	v_add_f32_e32 v89, v90, v89
	v_add_f32_e32 v90, v91, v92
	v_exp_f32_e32 v146, v146
	v_exp_f32_e32 v145, v145
	v_sub_f32_e32 v88, v88, v134
	v_sub_f32_e32 v87, v87, v134
	v_add_f32_e32 v89, v90, v89
	v_add_f32_e32 v90, v93, v94
	v_exp_f32_e32 v88, v88
	v_exp_f32_e32 v87, v87
	v_sub_f32_e32 v86, v86, v134
	v_sub_f32_e32 v85, v85, v134
	v_add_f32_e32 v89, v90, v89
	v_add_f32_e32 v90, v95, v96
	v_exp_f32_e32 v86, v86
	v_exp_f32_e32 v85, v85
	v_sub_f32_e32 v84, v84, v134
	v_sub_f32_e32 v83, v83, v134
	v_add_f32_e32 v89, v90, v89
	v_add_f32_e32 v90, v97, v144
	v_exp_f32_e32 v84, v84
	v_exp_f32_e32 v83, v83
	v_sub_f32_e32 v82, v82, v134
	v_sub_f32_e32 v76, v76, v134
	v_add_f32_e32 v89, v90, v89
	v_add_f32_e32 v90, v146, v145
	v_exp_f32_e32 v82, v82
	v_exp_f32_e32 v147, v76
	v_sub_f32_e32 v75, v75, v134
	v_sub_f32_e32 v74, v74, v134
	v_add_f32_e32 v89, v90, v89
	v_add_f32_e32 v90, v88, v87
	v_exp_f32_e32 v75, v75
	v_exp_f32_e32 v148, v74
	v_add_f32_e32 v89, v90, v89
	v_add_f32_e32 v90, v86, v85
	v_add_f32_e32 v89, v90, v89
	v_add_f32_e32 v90, v84, v83
	v_sub_f32_e32 v73, v73, v134
	v_sub_f32_e32 v72, v72, v134
	v_add_f32_e32 v74, v90, v89
	v_add_f32_e32 v76, v82, v147
	v_exp_f32_e32 v73, v73
	v_exp_f32_e32 v89, v72
	v_sub_f32_e32 v71, v71, v134
	v_sub_f32_e32 v70, v70, v134
	v_add_f32_e32 v74, v76, v74
	v_add_f32_e32 v76, v75, v148
	v_exp_f32_e32 v72, v71
	v_exp_f32_e32 v90, v70
	v_sub_f32_e32 v69, v69, v134
	v_sub_f32_e32 v68, v68, v134
	v_add_f32_e32 v70, v76, v74
	v_exp_f32_e32 v74, v69
	v_exp_f32_e32 v149, v68
	v_sub_f32_e32 v67, v67, v134
	v_sub_f32_e32 v66, v66, v134
	v_exp_f32_e32 v76, v67
	v_exp_f32_e32 v150, v66
	v_add_f32_e32 v71, v73, v89
	v_add_f32_e32 v70, v71, v70
	v_add_f32_e32 v71, v72, v90
	v_add_f32_e32 v66, v71, v70
	v_add_f32_e32 v67, v74, v149
	v_add_f32_e32 v66, v67, v66
	v_add_f32_e32 v67, v76, v150
	v_add_f32_e32 v151, v67, v66
	v_fmac_f32_e32 v151, v142, v77
	v_cvt_pk_bf16_f32 v66, v78, v80
	v_cvt_pk_bf16_f32 v67, v91, v93
	v_cvt_pk_bf16_f32 v68, v95, v97
	v_cvt_pk_bf16_f32 v69, v146, v88
	v_cvt_pk_bf16_f32 v70, v86, v84
	v_cvt_pk_bf16_f32 v71, v82, v75
	v_cvt_pk_bf16_f32 v72, v73, v72
	v_cvt_pk_bf16_f32 v73, v74, v76
	v_cvt_pk_bf16_f32 v74, v79, v81
	v_cvt_pk_bf16_f32 v75, v92, v94
	v_cvt_pk_bf16_f32 v76, v96, v144
	v_cvt_pk_bf16_f32 v77, v145, v87
	v_cvt_pk_bf16_f32 v78, v85, v83
	v_cvt_pk_bf16_f32 v79, v147, v148
	v_cvt_pk_bf16_f32 v80, v89, v90
	v_cvt_pk_bf16_f32 v81, v149, v150
	s_setprio 1
	v_add_u32_e32 v86, s50, v137
	ds_read_b64_tr_b16 v[82:83], v86 offset:16384
	ds_read_b64_tr_b16 v[84:85], v86 offset:16896
	s_waitcnt lgkmcnt(0)
	v_mfma_f32_32x32x16_bf16 v[18:33], v[66:69], v[82:85], v[18:33]
	ds_read_b64_tr_b16 v[82:83], v86 offset:17408
	ds_read_b64_tr_b16 v[84:85], v86 offset:17920
	s_waitcnt lgkmcnt(0)
	v_mfma_f32_32x32x16_bf16 v[18:33], v[70:73], v[82:85], v[18:33]
	ds_read_b64_tr_b16 v[82:83], v86 offset:18432
	ds_read_b64_tr_b16 v[84:85], v86 offset:18944
	s_waitcnt lgkmcnt(0)
	v_mfma_f32_32x32x16_bf16 v[18:33], v[74:77], v[82:85], v[18:33]
	ds_read_b64_tr_b16 v[82:83], v86 offset:19456
	ds_read_b64_tr_b16 v[84:85], v86 offset:19968
	s_waitcnt lgkmcnt(0)
	v_mfma_f32_32x32x16_bf16 v[18:33], v[78:81], v[82:85], v[18:33]
	ds_read_b64_tr_b16 v[82:83], v86 offset:20480
	ds_read_b64_tr_b16 v[84:85], v86 offset:20992
	s_waitcnt lgkmcnt(0)
	v_mfma_f32_32x32x16_bf16 v[2:17], v[66:69], v[82:85], v[2:17]
	ds_read_b64_tr_b16 v[66:67], v86 offset:21504
	ds_read_b64_tr_b16 v[68:69], v86 offset:22016
	s_waitcnt lgkmcnt(0)
	v_mfma_f32_32x32x16_bf16 v[2:17], v[70:73], v[66:69], v[2:17]
	ds_read_b64_tr_b16 v[66:67], v86 offset:22528
	ds_read_b64_tr_b16 v[68:69], v86 offset:23040
	s_waitcnt lgkmcnt(0)
	v_mfma_f32_32x32x16_bf16 v[2:17], v[74:77], v[66:69], v[2:17]
	ds_read_b64_tr_b16 v[66:67], v86 offset:23552
	ds_read_b64_tr_b16 v[68:69], v86 offset:24064
	s_waitcnt lgkmcnt(0)
	v_mfma_f32_32x32x16_bf16 v[2:17], v[78:81], v[66:69], v[2:17]
	s_setprio 0
	v_mov_b32_e32 v142, v151
	s_branch .LBB0_469

; __device__ __forceinline__ void softmax_pv(f32x16& p0, f32x16& p1, float& m, float& l, f32x16 (&o)[2], LAS float* wsf, const LAS unsigned char* vp, int r32, int hi) {
;     float rm = fmaxf(p0[0], p1[0]);
; #pragma unroll
;     for (int r = 1; r < 16; ++r) rm = fmaxf(rm, fmaxf(p0[r], p1[r]));
;     rm = pair_max(rm);
;     if (__all(rm - m < -151.0f)) return;
; template <int VAR>
; __device__ __forceinline__ void attn_unit(LAS unsigned char* lds, const AttnArgs& A, int b, int h, int qb, const int tid) {
;     ...
;                 f32x16 p0, p1;
; #pragma unroll
;                 for (int r = 0; r < 16; ++r) { p0[r] = 0.f; p1[r] = 0.f; }
;                 __builtin_amdgcn_s_setprio(1);
; #pragma unroll
;                 for (int d0 = 0; d0 < 4; ++d0) {
;                     const bf16x8 b0 = *(const LAS bf16x8*)(kb + d0 * 2048), b1 = *(const LAS bf16x8*)(kb + d0 * 2048 + 512);
;                     p0 = __builtin_amdgcn_mfma_f32_32x32x16_bf16(b0, qr[d0], p0, 0, 0, 0);
;                     p1 = __builtin_amdgcn_mfma_f32_32x32x16_bf16(b1, qr[d0], p1, 0, 0, 0);
;                 }
;                 __builtin_amdgcn_s_setprio(0);
;                 if (VAR == 0) {
;                     const LAS float* fs = FS + buf * 64 + 4 * hi;
; #pragma unroll
;                     for (int a = 0; a < 4; ++a) {
;                         const f32x4 f0 = *(const LAS f32x4*)(fs + 8 * a), f1 = *(const LAS f32x4*)(fs + 32 + 8 * a);
; #pragma unroll
;                         for (int j = 0; j < 4; ++j) { p0[4 * a + j] += Ft - f0[j]; p1[4 * a + j] += Ft - f1[j]; }
;                     }
;                     if (diag) {
;                         const float tlf = (float)tl;
; #pragma unroll
;                         for (int r = 0; r < 16; ++r) { const float c0 = (float)((r & 3) + 8 * (r >> 2));
;                             p0[r] = __builtin_fmaf(fminf(tlf - c0, 0.f), 1e30f, p0[r]); p1[r] = __builtin_fmaf(fminf(tlf - (c0 + 32.0f), 0.f), 1e30f, p1[r]); }
;                     }
;                     softmax_pv(p0, p1, m1, l1, o, wsf, vp, r32, hi);
;                     wdone = __all(qkb1 + (Ft - FS[buf * 64]) - m1 < -151.0f);
;                 } else if (VAR == 1) {
;                     const LAS float* eb = EXTL + (576 - tl);
; #pragma unroll
;                     for (int r = 0; r < 16; ++r) { const int c0 = (r & 3) + 8 * (r >> 2); p0[r] += eb[c0]; p1[r] += eb[c0 + 32]; }
.LBB0_489:
	s_add_i32 s38, s71, 2
	s_cmp_gt_i32 s38, s11
	s_cselect_b64 s[12:13], -1, 0
	s_cmp_lt_i32 s38, s28
	s_cselect_b64 s[38:39], -1, 0
	s_or_b64 s[12:13], s[12:13], s[38:39]
	s_and_b64 vcc, exec, s[12:13]
	s_cbranch_vccnz .LBB0_496
	s_add_i32 s12, s81, 0xffffe000
	s_and_b32 s50, s12, 0x2000
	v_add_u32_e32 v108, s50, v97
	s_setprio 1
	ds_read_b128 v[126:129], v108
	ds_read_b128 v[130:133], v108 offset:2048
	ds_read_b128 v[134:137], v108 offset:512
	ds_read_b128 v[138:141], v108 offset:2560
	ds_read_b128 v[146:149], v108 offset:4096
	ds_read_b128 v[150:153], v108 offset:4608
	ds_read_b128 v[166:169], v108 offset:6144
	ds_read_b128 v[170:173], v108 offset:6656
	s_waitcnt lgkmcnt(7)
	v_mfma_f32_32x32x16_bf16 v[34:49], v[126:129], v[66:69], 0
	s_waitcnt lgkmcnt(6)
	v_mfma_f32_32x32x16_bf16 v[34:49], v[130:133], v[70:73], v[34:49]
	s_waitcnt lgkmcnt(5)
	v_mfma_f32_32x32x16_bf16 v[50:65], v[134:137], v[66:69], 0
	s_waitcnt lgkmcnt(4)
	v_mfma_f32_32x32x16_bf16 v[50:65], v[138:141], v[70:73], v[50:65]
	s_waitcnt lgkmcnt(3)
	v_mfma_f32_32x32x16_bf16 v[34:49], v[146:149], v[74:77], v[34:49]
	s_waitcnt lgkmcnt(2)
	v_mfma_f32_32x32x16_bf16 v[50:65], v[150:153], v[74:77], v[50:65]
	s_waitcnt lgkmcnt(1)
	v_mfma_f32_32x32x16_bf16 v[34:49], v[166:169], v[78:81], v[34:49]
	s_waitcnt lgkmcnt(0)
	v_mfma_f32_32x32x16_bf16 v[50:65], v[170:173], v[78:81], v[50:65]
	s_setprio 0
	ds_read2_b32 v[206:207], v101 offset1:1
	ds_read2_b32 v[208:209], v101 offset0:32 offset1:33
	ds_read2_b32 v[210:211], v101 offset0:34 offset1:35
	ds_read2_b32 v[212:213], v101 offset0:2 offset1:3
	ds_read2_b32 v[214:215], v101 offset0:8 offset1:9
	ds_read2_b32 v[216:217], v101 offset0:40 offset1:41
	ds_read2_b32 v[218:219], v101 offset0:10 offset1:11
	ds_read2_b32 v[220:221], v101 offset0:42 offset1:43
	ds_read2_b32 v[222:223], v101 offset0:16 offset1:17
	ds_read2_b32 v[224:225], v101 offset0:48 offset1:49
	ds_read2_b32 v[226:227], v101 offset0:18 offset1:19
	ds_read2_b32 v[228:229], v101 offset0:50 offset1:51
	ds_read2_b32 v[230:231], v101 offset0:24 offset1:25
	ds_read2_b32 v[232:233], v101 offset0:56 offset1:57
	ds_read2_b32 v[234:235], v101 offset0:26 offset1:27
	ds_read2_b32 v[236:237], v101 offset0:58 offset1:59
	s_waitcnt lgkmcnt(15)
	v_add_f32_e32 v34, v34, v206
	s_waitcnt lgkmcnt(14)
	v_add_f32_e32 v104, v50, v208
	v_add_f32_e32 v50, v35, v207
	v_add_f32_e32 v35, v51, v209
	s_waitcnt lgkmcnt(13)
	v_add_f32_e32 v52, v52, v210
	s_waitcnt lgkmcnt(12)
	v_add_f32_e32 v51, v36, v212
	v_add_f32_e32 v37, v37, v213
	v_add_f32_e32 v36, v53, v211
	s_waitcnt lgkmcnt(11)
	v_add_f32_e32 v105, v38, v214
	s_waitcnt lgkmcnt(10)
	v_add_f32_e32 v54, v54, v216
	v_add_f32_e32 v53, v39, v215
	v_add_f32_e32 v39, v55, v217
	v_max_f32_e32 v38, v50, v35
	v_max3_f32 v38, v34, v104, v38
	s_waitcnt lgkmcnt(9)
	v_add_f32_e32 v40, v40, v218
	s_waitcnt lgkmcnt(8)
	v_add_f32_e32 v56, v56, v220
	v_add_f32_e32 v55, v41, v219
	v_add_f32_e32 v41, v57, v221
	s_waitcnt lgkmcnt(7)
	v_add_f32_e32 v42, v42, v222
	s_waitcnt lgkmcnt(6)
	v_add_f32_e32 v58, v58, v224
	v_add_f32_e32 v57, v43, v223
	v_add_f32_e32 v43, v59, v225
	s_waitcnt lgkmcnt(5)
	v_add_f32_e32 v59, v44, v226
	s_waitcnt lgkmcnt(4)
	v_add_f32_e32 v60, v60, v228
	v_add_f32_e32 v45, v45, v227
	v_add_f32_e32 v44, v61, v229
	s_waitcnt lgkmcnt(3)
	v_add_f32_e32 v61, v46, v230
	s_waitcnt lgkmcnt(2)
	v_add_f32_e32 v62, v62, v232
	v_add_f32_e32 v47, v47, v231
	v_add_f32_e32 v46, v63, v233
	s_waitcnt lgkmcnt(1)
	v_add_f32_e32 v48, v48, v234
	v_add_f32_e32 v63, v49, v235
	s_waitcnt lgkmcnt(0)
	v_add_u32_e32 v194, s50, v99
	ds_read_b64_tr_b16 v[238:239], v194 offset:16384
	ds_read_b64_tr_b16 v[240:241], v194 offset:16896
	ds_read_b64_tr_b16 v[242:243], v194 offset:17408
	ds_read_b64_tr_b16 v[244:245], v194 offset:17920
	ds_read_b64_tr_b16 v[246:247], v194 offset:18432
	ds_read_b64_tr_b16 v[248:249], v194 offset:18944
	ds_read_b64_tr_b16 v[250:251], v194 offset:19456
	ds_read_b64_tr_b16 v[252:253], v194 offset:19968
	ds_read_b64_tr_b16 v[178:179], v194 offset:20480
	ds_read_b64_tr_b16 v[180:181], v194 offset:20992
	ds_read_b64_tr_b16 v[182:183], v194 offset:21504
	ds_read_b64_tr_b16 v[184:185], v194 offset:22016
	ds_read_b64_tr_b16 v[186:187], v194 offset:22528
	ds_read_b64_tr_b16 v[188:189], v194 offset:23040
	ds_read_b64_tr_b16 v[190:191], v194 offset:23552
	ds_read_b64_tr_b16 v[192:193], v194 offset:24064
	v_add_f32_e32 v49, v65, v237
	v_max_f32_e32 v65, v51, v52
	v_max_f32_e32 v106, v37, v36
	v_max3_f32 v38, v38, v65, v106
	v_max_f32_e32 v65, v105, v54
	v_max_f32_e32 v106, v53, v39
	v_max3_f32 v38, v38, v65, v106
	v_max_f32_e32 v65, v40, v56
	v_max_f32_e32 v106, v55, v41
	v_max3_f32 v38, v38, v65, v106
	v_max_f32_e32 v65, v42, v58
	v_max_f32_e32 v106, v57, v43
	v_max3_f32 v38, v38, v65, v106
	v_max_f32_e32 v65, v59, v60
	v_max_f32_e32 v106, v45, v44
	v_add_f32_e32 v64, v64, v236
	v_max3_f32 v38, v38, v65, v106
	v_max_f32_e32 v65, v61, v62
	v_max_f32_e32 v106, v47, v46
	v_max3_f32 v38, v38, v65, v106
	v_max_f32_e32 v65, v48, v64
	v_max_f32_e32 v106, v63, v49
	v_max3_f32 v38, v38, v65, v106
	v_mov_b32_e32 v65, v38
	s_nop 1
	v_permlane32_swap_b32_e32 v38, v65
	v_max_f32_e32 v65, v65, v65
	v_max_f32_e32 v38, v38, v38
	v_max_f32_e32 v38, v38, v65
	v_sub_f32_e32 v65, v38, v103
	v_cmp_gt_f32_e32 vcc, s36, v65
	s_cmp_eq_u64 vcc, exec
	s_cbranch_scc1 .LBB0_496
	v_max_f32_e32 v38, v38, v38
	v_max_f32_e32 v65, v103, v103
	v_max_f32_e32 v38, v65, v38
	v_sub_f32_e32 v65, v103, v38
	v_exp_f32_e32 v65, v65
	s_nop 0
	v_cmp_neq_f32_e32 vcc, 1.0, v65
	s_cbranch_vccz .LBB0_495
	s_and_saveexec_b64 s[12:13], s[8:9]
	ds_write_b32 v100, v65 offset:36864
	s_or_b64 exec, exec, s[12:13]
	v_add_u32_e32 v103, s68, v0
	ds_read_b128 v[106:109], v103 offset:36960
	ds_read_b128 v[110:113], v103 offset:36928
	ds_read_b128 v[114:117], v103 offset:36896
	ds_read_b128 v[118:121], v103 offset:36864
	s_waitcnt lgkmcnt(3)
	v_pk_mul_f32 v[30:31], v[30:31], v[106:107]
	s_waitcnt lgkmcnt(2)
	v_pk_mul_f32 v[26:27], v[26:27], v[110:111]
	s_waitcnt lgkmcnt(1)
	v_pk_mul_f32 v[22:23], v[22:23], v[114:115]
	s_waitcnt lgkmcnt(0)
	v_pk_mul_f32 v[18:19], v[18:19], v[118:119]
	v_pk_mul_f32 v[14:15], v[14:15], v[106:107]
	v_pk_mul_f32 v[10:11], v[10:11], v[110:111]
	v_pk_mul_f32 v[6:7], v[6:7], v[114:115]
	v_pk_mul_f32 v[32:33], v[32:33], v[108:109]
	v_pk_mul_f32 v[28:29], v[28:29], v[112:113]
	v_pk_mul_f32 v[24:25], v[24:25], v[116:117]
	v_pk_mul_f32 v[20:21], v[20:21], v[120:121]
	v_pk_mul_f32 v[16:17], v[16:17], v[108:109]
	v_pk_mul_f32 v[12:13], v[12:13], v[112:113]
	v_pk_mul_f32 v[8:9], v[8:9], v[116:117]
	v_pk_mul_f32 v[4:5], v[4:5], v[120:121]
	v_pk_mul_f32 v[2:3], v[2:3], v[118:119]
; #define LAS __attribute__((address_space(3)))
; __device__ __forceinline__ unsigned cvtpk(float lo, float hi) { f32x2_t v = {lo, hi}; bf16x2_t b = __builtin_convertvector(v, bf16x2_t); return __builtin_bit_cast(unsigned, b); }
; __device__ __forceinline__ s16x4 vtr(const LAS unsigned char* p) { return __builtin_bit_cast(s16x4, __builtin_amdgcn_ds_read_tr16_b64_v4i16((LAS v4i16_t*)p)); }
; __device__ __forceinline__ void pv(f32x16 (&o)[2], const LAS unsigned char* vp, const f32x16& p0, const f32x16& p1) {
;     u32x4 pw[4];
;     pw[0] = (u32x4){cvtpk(p0[0], p0[1]), cvtpk(p0[2], p0[3]), cvtpk(p0[4], p0[5]), cvtpk(p0[6], p0[7])};
;     pw[1] = (u32x4){cvtpk(p0[8], p0[9]), cvtpk(p0[10], p0[11]), cvtpk(p0[12], p0[13]), cvtpk(p0[14], p0[15])};
;     pw[2] = (u32x4){cvtpk(p1[0], p1[1]), cvtpk(p1[2], p1[3]), cvtpk(p1[4], p1[5]), cvtpk(p1[6], p1[7])};
;     pw[3] = (u32x4){cvtpk(p1[8], p1[9]), cvtpk(p1[10], p1[11]), cvtpk(p1[12], p1[13]), cvtpk(p1[14], p1[15])};
;     __builtin_amdgcn_s_setprio(1);
; #pragma unroll
;     for (int dh = 0; dh < 2; ++dh)
; #pragma unroll
;         for (int ks = 0; ks < 4; ++ks) {
;             const s16x4 lo = vtr(vp + dh * 4096 + ks * 1024), hi_ = vtr(vp + dh * 4096 + ks * 1024 + 512);
;             const bf16x8 vf = __builtin_shufflevector(lo, hi_, 0, 1, 2, 3, 4, 5, 6, 7);
;             o[dh] = __builtin_amdgcn_mfma_f32_32x32x16_bf16(__builtin_bit_cast(bf16x8, pw[ks]), vf, o[dh], 0, 0, 0);
;         }
;     __builtin_amdgcn_s_setprio(0);
; __device__ __forceinline__ void softmax_pv(f32x16& p0, f32x16& p1, float& m, float& l, f32x16 (&o)[2], LAS float* wsf, const LAS unsigned char* vp, int r32, int hi) {
;     ...
;     float s = 0.f;
; #pragma unroll
;     for (int r = 0; r < 16; ++r) { p0[r] = __builtin_amdgcn_exp2f(p0[r] - mnew); p1[r] = __builtin_amdgcn_exp2f(p1[r] - mnew); s += p0[r] + p1[r]; }
;     l = l * alpha + s;
.LBB0_495:
	v_sub_f32_e32 v34, v34, v38
	v_sub_f32_e32 v103, v104, v38
	v_exp_f32_e32 v34, v34
	v_exp_f32_e32 v103, v103
	v_sub_f32_e32 v50, v50, v38
	v_sub_f32_e32 v35, v35, v38
	v_exp_f32_e32 v50, v50
	v_exp_f32_e32 v104, v35
	v_sub_f32_e32 v51, v51, v38
	v_sub_f32_e32 v52, v52, v38
	v_exp_f32_e32 v51, v51
	v_exp_f32_e32 v52, v52
	v_sub_f32_e32 v37, v37, v38
	v_sub_f32_e32 v36, v36, v38
	v_exp_f32_e32 v37, v37
	v_exp_f32_e32 v107, v36
	v_sub_f32_e32 v105, v105, v38
	v_sub_f32_e32 v54, v54, v38
	v_add_f32_e32 v35, v34, v103
	v_exp_f32_e32 v105, v105
	v_exp_f32_e32 v54, v54
	v_sub_f32_e32 v53, v53, v38
	v_sub_f32_e32 v39, v39, v38
	v_add_f32_e32 v35, 0, v35
	v_add_f32_e32 v106, v50, v104
	v_exp_f32_e32 v53, v53
	v_exp_f32_e32 v39, v39
	v_sub_f32_e32 v40, v40, v38
	v_sub_f32_e32 v56, v56, v38
	v_add_f32_e32 v35, v106, v35
	v_add_f32_e32 v36, v51, v52
	v_exp_f32_e32 v40, v40
	v_exp_f32_e32 v56, v56
	v_sub_f32_e32 v55, v55, v38
	v_sub_f32_e32 v41, v41, v38
	v_add_f32_e32 v35, v36, v35
	v_add_f32_e32 v36, v37, v107
	v_exp_f32_e32 v55, v55
	v_exp_f32_e32 v106, v41
	v_sub_f32_e32 v41, v42, v38
	v_sub_f32_e32 v42, v58, v38
	v_add_f32_e32 v35, v36, v35
	v_add_f32_e32 v36, v105, v54
	v_exp_f32_e32 v41, v41
	v_exp_f32_e32 v58, v42
	v_sub_f32_e32 v42, v57, v38
	v_sub_f32_e32 v43, v43, v38
	v_add_f32_e32 v35, v36, v35
	v_add_f32_e32 v36, v53, v39
	v_exp_f32_e32 v42, v42
	v_exp_f32_e32 v57, v43
	v_sub_f32_e32 v43, v59, v38
	v_sub_f32_e32 v59, v60, v38
	v_add_f32_e32 v35, v36, v35
	v_add_f32_e32 v36, v40, v56
	v_exp_f32_e32 v43, v43
	v_exp_f32_e32 v59, v59
	v_sub_f32_e32 v45, v45, v38
	v_sub_f32_e32 v44, v44, v38
	v_add_f32_e32 v35, v36, v35
	v_add_f32_e32 v36, v55, v106
	v_exp_f32_e32 v45, v45
	v_exp_f32_e32 v60, v44
	v_sub_f32_e32 v44, v61, v38
	v_sub_f32_e32 v61, v62, v38
	v_add_f32_e32 v35, v36, v35
	v_add_f32_e32 v36, v41, v58
	v_exp_f32_e32 v44, v44
	v_exp_f32_e32 v61, v61
	v_sub_f32_e32 v47, v47, v38
	v_sub_f32_e32 v46, v46, v38
	v_add_f32_e32 v35, v36, v35
	v_add_f32_e32 v36, v42, v57
	v_exp_f32_e32 v47, v47
	v_exp_f32_e32 v62, v46
	v_sub_f32_e32 v46, v48, v38
	v_sub_f32_e32 v48, v64, v38
	v_add_f32_e32 v35, v36, v35
	v_add_f32_e32 v36, v43, v59
	v_exp_f32_e32 v46, v46
	v_exp_f32_e32 v64, v48
	v_sub_f32_e32 v48, v63, v38
	v_sub_f32_e32 v49, v49, v38
	v_add_f32_e32 v35, v36, v35
	v_add_f32_e32 v36, v45, v60
	v_exp_f32_e32 v48, v48
	v_exp_f32_e32 v63, v49
	v_add_f32_e32 v35, v36, v35
	v_add_f32_e32 v36, v44, v61
	v_add_f32_e32 v35, v36, v35
	v_add_f32_e32 v36, v47, v62
	v_add_f32_e32 v35, v36, v35
	v_add_f32_e32 v36, v46, v64
	v_add_f32_e32 v35, v36, v35
	v_add_f32_e32 v36, v48, v63
	v_add_f32_e32 v108, v36, v35
	v_fmac_f32_e32 v108, v102, v65
	v_cvt_pk_bf16_f32 v34, v34, v50
	v_cvt_pk_bf16_f32 v35, v51, v37
	v_cvt_pk_bf16_f32 v36, v105, v53
	v_cvt_pk_bf16_f32 v37, v40, v55
	v_cvt_pk_bf16_f32 v40, v41, v42
	v_cvt_pk_bf16_f32 v41, v43, v45
	v_cvt_pk_bf16_f32 v42, v44, v47
	v_cvt_pk_bf16_f32 v43, v46, v48
	v_cvt_pk_bf16_f32 v44, v103, v104
	v_cvt_pk_bf16_f32 v45, v52, v107
	v_cvt_pk_bf16_f32 v46, v54, v39
	v_cvt_pk_bf16_f32 v47, v56, v106
	v_cvt_pk_bf16_f32 v48, v58, v57
	v_cvt_pk_bf16_f32 v49, v59, v60
	v_cvt_pk_bf16_f32 v50, v61, v62
	v_cvt_pk_bf16_f32 v51, v64, v63
	s_setprio 1
	s_waitcnt lgkmcnt(0)
	v_mfma_f32_32x32x16_bf16 v[2:17], v[34:37], v[238:241], v[2:17]
	v_mfma_f32_32x32x16_bf16 v[2:17], v[40:43], v[242:245], v[2:17]
	v_mfma_f32_32x32x16_bf16 v[2:17], v[44:47], v[246:249], v[2:17]
	v_mfma_f32_32x32x16_bf16 v[2:17], v[48:51], v[250:253], v[2:17]
	v_mfma_f32_32x32x16_bf16 v[18:33], v[34:37], v[178:181], v[18:33]
	v_mfma_f32_32x32x16_bf16 v[18:33], v[40:43], v[182:185], v[18:33]
	v_mfma_f32_32x32x16_bf16 v[18:33], v[44:47], v[186:189], v[18:33]
	v_mfma_f32_32x32x16_bf16 v[18:33], v[48:51], v[190:193], v[18:33]
	s_setprio 0
	v_mov_b32_e32 v102, v108
	v_mov_b32_e32 v103, v38
